# attention output stores: plain -> sc0 sc1 write-through (no dirty lines left for the phase-3 barrier write-back)
# speedup vs baseline: 1.0019x; 1.0019x over previous
; DI void dattn_unit2(const bf16_t* __restrict__ Qg, const bf16_t* __restrict__ Kg, const bf16_t* __restrict__ Vg, bf16_t* __restrict__ Og,
;                     int ntiles, int wave_tiles, float lam, const float* __restrict__ gsub, lds_t* shm) {
;     ...
;   const float l0 = lrun[0] + __shfl_xor(lrun[0], 32), l1 = lrun[1] + __shfl_xor(lrun[1], 32);
;   const float i0 = 1.0f / l0, i1 = lam / l1;
;   float ssq = 0.f;
; #pragma unroll
;   for (int c = 0; c < NC; ++c)
; #pragma unroll
;     for (int i = 0; i < 16; ++i) { const float a = O[0][c][i] * i0 - O[1][c][i] * i1; O[0][c][i] = a; ssq += a * a; }
;   ssq += __shfl_xor(ssq, 32);
;   const float inv = rsqrtf(ssq * (1.0f / 128.0f) + RMS_EPS) * 0.8f;
.LBB0_414:
	ds_bpermute_b32 v128, v213, v201
	ds_bpermute_b32 v129, v213, v200
	s_lshl_b64 s[4:5], s[42:43], 1
	s_add_u32 s4, s35, s4
	s_addc_u32 s5, s46, s5
	s_waitcnt lgkmcnt(0)
	v_add_f32_e32 v128, v201, v128
	v_div_scale_f32 v130, s[6:7], v128, v128, 1.0
	v_rcp_f32_e32 v131, v130
	v_add_f32_e32 v129, v200, v129
	v_fma_f32 v132, -v130, v131, 1.0
	v_fmac_f32_e32 v131, v132, v131
	v_div_scale_f32 v132, vcc, 1.0, v128, 1.0
	v_mul_f32_e32 v133, v132, v131
	v_fma_f32 v134, -v130, v133, v132
	v_fmac_f32_e32 v133, v134, v131
	v_fma_f32 v130, -v130, v133, v132
	v_div_scale_f32 v132, s[6:7], v129, v129, v215
	v_rcp_f32_e32 v134, v132
	v_div_fmas_f32 v130, v130, v131, v133
	v_div_fixup_f32 v138, v130, v128, 1.0
	v_fma_f32 v128, -v132, v134, 1.0
	v_fmac_f32_e32 v134, v128, v134
	v_div_scale_f32 v128, vcc, v215, v129, v215
	v_mul_f32_e32 v130, v128, v134
	v_fma_f32 v131, -v132, v130, v128
	v_fmac_f32_e32 v130, v131, v134
	v_fma_f32 v128, -v132, v130, v128
	v_div_fmas_f32 v128, v128, v134, v130
	v_div_fixup_f32 v140, v128, v129, v215
	v_pk_mul_f32 v[28:29], v[28:29], v[140:141] op_sel_hi:[1,0]
	s_nop 0
	v_pk_fma_f32 v[128:129], v[12:13], v[138:139], v[28:29] op_sel_hi:[1,0,1] neg_lo:[0,0,1] neg_hi:[0,0,1]
	v_pk_mul_f32 v[12:13], v[30:31], v[140:141] op_sel_hi:[1,0]
	v_pk_mul_f32 v[134:135], v[128:129], v[128:129]
	v_pk_fma_f32 v[130:131], v[14:15], v[138:139], v[12:13] op_sel_hi:[1,0,1] neg_lo:[0,0,1] neg_hi:[0,0,1]
	v_mov_b32_e32 v139, v212
	v_pk_mul_f32 v[136:137], v[130:131], v[130:131]
	v_bfe_u32 v141, v139, 5, 1
	v_pk_mul_f32 v[12:13], v[112:113], v[140:141] op_sel_hi:[1,0]
	v_pk_mul_f32 v[28:29], v[80:81], v[140:141] op_sel_hi:[1,0]
	v_pk_fma_f32 v[112:113], v[96:97], v[138:139], v[12:13] op_sel_hi:[1,0,1] neg_lo:[0,0,1] neg_hi:[0,0,1]
	v_pk_mul_f32 v[12:13], v[114:115], v[140:141] op_sel_hi:[1,0]
	v_pk_fma_f32 v[80:81], v[64:65], v[138:139], v[28:29] op_sel_hi:[1,0,1] neg_lo:[0,0,1] neg_hi:[0,0,1]
	v_pk_fma_f32 v[132:133], v[98:99], v[138:139], v[12:13] op_sel_hi:[1,0,1] neg_lo:[0,0,1] neg_hi:[0,0,1]
	v_pk_mul_f32 v[12:13], v[116:117], v[140:141] op_sel_hi:[1,0]
	v_pk_mul_f32 v[28:29], v[82:83], v[140:141] op_sel_hi:[1,0]
	v_pk_fma_f32 v[114:115], v[100:101], v[138:139], v[12:13] op_sel_hi:[1,0,1] neg_lo:[0,0,1] neg_hi:[0,0,1]
	v_pk_mul_f32 v[12:13], v[118:119], v[140:141] op_sel_hi:[1,0]
	v_pk_fma_f32 v[82:83], v[66:67], v[138:139], v[28:29] op_sel_hi:[1,0,1] neg_lo:[0,0,1] neg_hi:[0,0,1]
	v_pk_mul_f32 v[28:29], v[84:85], v[140:141] op_sel_hi:[1,0]
	v_pk_fma_f32 v[118:119], v[102:103], v[138:139], v[12:13] op_sel_hi:[1,0,1] neg_lo:[0,0,1] neg_hi:[0,0,1]
	v_pk_mul_f32 v[12:13], v[120:121], v[140:141] op_sel_hi:[1,0]
	v_pk_fma_f32 v[84:85], v[68:69], v[138:139], v[28:29] op_sel_hi:[1,0,1] neg_lo:[0,0,1] neg_hi:[0,0,1]
	v_pk_mul_f32 v[68:69], v[88:89], v[140:141] op_sel_hi:[1,0]
	v_pk_fma_f32 v[116:117], v[104:105], v[138:139], v[12:13] op_sel_hi:[1,0,1] neg_lo:[0,0,1] neg_hi:[0,0,1]
	v_pk_mul_f32 v[12:13], v[122:123], v[140:141] op_sel_hi:[1,0]
	v_pk_fma_f32 v[88:89], v[72:73], v[138:139], v[68:69] op_sel_hi:[1,0,1] neg_lo:[0,0,1] neg_hi:[0,0,1]
	v_pk_mul_f32 v[68:69], v[90:91], v[140:141] op_sel_hi:[1,0]
	v_pk_fma_f32 v[122:123], v[106:107], v[138:139], v[12:13] op_sel_hi:[1,0,1] neg_lo:[0,0,1] neg_hi:[0,0,1]
	v_pk_mul_f32 v[12:13], v[124:125], v[140:141] op_sel_hi:[1,0]
	v_pk_fma_f32 v[90:91], v[74:75], v[138:139], v[68:69] op_sel_hi:[1,0,1] neg_lo:[0,0,1] neg_hi:[0,0,1]
	v_pk_mul_f32 v[68:69], v[92:93], v[140:141] op_sel_hi:[1,0]
	v_pk_mul_f32 v[48:49], v[48:49], v[140:141] op_sel_hi:[1,0]
	v_pk_mul_f32 v[142:143], v[112:113], v[112:113]
	v_pk_fma_f32 v[120:121], v[108:109], v[138:139], v[12:13] op_sel_hi:[1,0,1] neg_lo:[0,0,1] neg_hi:[0,0,1]
	v_pk_mul_f32 v[12:13], v[126:127], v[140:141] op_sel_hi:[1,0]
	v_pk_mul_f32 v[28:29], v[86:87], v[140:141] op_sel_hi:[1,0]
	v_pk_fma_f32 v[76:77], v[76:77], v[138:139], v[68:69] op_sel_hi:[1,0,1] neg_lo:[0,0,1] neg_hi:[0,0,1]
	v_pk_mul_f32 v[68:69], v[94:95], v[140:141] op_sel_hi:[1,0]
	v_pk_fma_f32 v[48:49], v[32:33], v[138:139], v[48:49] op_sel_hi:[1,0,1] neg_lo:[0,0,1] neg_hi:[0,0,1]
	v_pk_mul_f32 v[32:33], v[50:51], v[140:141] op_sel_hi:[1,0]
	v_pk_mul_f32 v[52:53], v[52:53], v[140:141] op_sel_hi:[1,0]
	v_pk_mul_f32 v[54:55], v[54:55], v[140:141] op_sel_hi:[1,0]
	v_pk_mul_f32 v[56:57], v[56:57], v[140:141] op_sel_hi:[1,0]
	v_pk_mul_f32 v[58:59], v[58:59], v[140:141] op_sel_hi:[1,0]
	v_pk_mul_f32 v[60:61], v[60:61], v[140:141] op_sel_hi:[1,0]
	v_pk_mul_f32 v[62:63], v[62:63], v[140:141] op_sel_hi:[1,0]
	v_pk_mul_f32 v[16:17], v[16:17], v[140:141] op_sel_hi:[1,0]
	v_pk_mul_f32 v[18:19], v[18:19], v[140:141] op_sel_hi:[1,0]
	v_pk_mul_f32 v[20:21], v[20:21], v[140:141] op_sel_hi:[1,0]
	v_pk_mul_f32 v[22:23], v[22:23], v[140:141] op_sel_hi:[1,0]
	v_pk_mul_f32 v[24:25], v[24:25], v[140:141] op_sel_hi:[1,0]
	v_pk_mul_f32 v[26:27], v[26:27], v[140:141] op_sel_hi:[1,0]
	v_lshlrev_b32_e32 v168, 4, v141
	v_pk_mul_f32 v[144:145], v[132:133], v[132:133]
	v_pk_fma_f32 v[108:109], v[110:111], v[138:139], v[12:13] op_sel_hi:[1,0,1] neg_lo:[0,0,1] neg_hi:[0,0,1]
	v_pk_fma_f32 v[86:87], v[70:71], v[138:139], v[28:29] op_sel_hi:[1,0,1] neg_lo:[0,0,1] neg_hi:[0,0,1]
	v_pk_fma_f32 v[78:79], v[78:79], v[138:139], v[68:69] op_sel_hi:[1,0,1] neg_lo:[0,0,1] neg_hi:[0,0,1]
	v_pk_fma_f32 v[50:51], v[34:35], v[138:139], v[32:33] op_sel_hi:[1,0,1] neg_lo:[0,0,1] neg_hi:[0,0,1]
	v_pk_fma_f32 v[36:37], v[36:37], v[138:139], v[52:53] op_sel_hi:[1,0,1] neg_lo:[0,0,1] neg_hi:[0,0,1]
	v_pk_fma_f32 v[38:39], v[38:39], v[138:139], v[54:55] op_sel_hi:[1,0,1] neg_lo:[0,0,1] neg_hi:[0,0,1]
; DI int tidx() { int t = threadIdx.x; asm volatile("" : "+v"(t)); return t; }
; DI unsigned pk2(float lo, float hi) { bf2_t v = __builtin_convertvector((f32x2){lo, hi}, bf2_t); return __builtin_bit_cast(unsigned, v); }
; DI void dattn_unit2(const bf16_t* __restrict__ Qg, const bf16_t* __restrict__ Kg, const bf16_t* __restrict__ Vg, bf16_t* __restrict__ Og,
;                     int ntiles, int wave_tiles, float lam, const float* __restrict__ gsub, lds_t* shm) {
;     ...
;     for (int i = 0; i < 16; ++i) { const float a = O[0][c][i] * i0 - O[1][c][i] * i1; O[0][c][i] = a; ssq += a * a; }
;   ssq += __shfl_xor(ssq, 32);
;   const float inv = rsqrtf(ssq * (1.0f / 128.0f) + RMS_EPS) * 0.8f;
;   const int lane_f = tidx() & 63, h_f = lane_f >> 5;
;   const unsigned ooff = ((unsigned)(lane_f & 31) * (unsigned)LD + 4u * h_f) * 2u;
; #pragma unroll
;   for (int c = 0; c < NC; ++c)
; #pragma unroll
;     for (int g4 = 0; g4 < 4; ++g4) {
;       const int dv0 = 32 * c + 8 * g4; f32x4 o;
; #pragma unroll
;       for (int e = 0; e < 4; ++e) o[e] = O[0][c][4 * g4 + e] * inv;
;       o = o * gld<f32x4>(gsub + dv0, 16u * h_f);
;       u32x2 w; w.x = pk2(o[0], o[1]); w.y = pk2(o[2], o[3]);
	v_pk_fma_f32 v[40:41], v[40:41], v[138:139], v[56:57] op_sel_hi:[1,0,1] neg_lo:[0,0,1] neg_hi:[0,0,1]
	v_pk_fma_f32 v[42:43], v[42:43], v[138:139], v[58:59] op_sel_hi:[1,0,1] neg_lo:[0,0,1] neg_hi:[0,0,1]
	v_pk_fma_f32 v[44:45], v[44:45], v[138:139], v[60:61] op_sel_hi:[1,0,1] neg_lo:[0,0,1] neg_hi:[0,0,1]
	v_pk_fma_f32 v[46:47], v[46:47], v[138:139], v[62:63] op_sel_hi:[1,0,1] neg_lo:[0,0,1] neg_hi:[0,0,1]
	v_pk_fma_f32 v[0:1], v[0:1], v[138:139], v[16:17] op_sel_hi:[1,0,1] neg_lo:[0,0,1] neg_hi:[0,0,1]
	v_pk_fma_f32 v[2:3], v[2:3], v[138:139], v[18:19] op_sel_hi:[1,0,1] neg_lo:[0,0,1] neg_hi:[0,0,1]
	v_pk_fma_f32 v[4:5], v[4:5], v[138:139], v[20:21] op_sel_hi:[1,0,1] neg_lo:[0,0,1] neg_hi:[0,0,1]
	v_pk_fma_f32 v[6:7], v[6:7], v[138:139], v[22:23] op_sel_hi:[1,0,1] neg_lo:[0,0,1] neg_hi:[0,0,1]
	v_pk_fma_f32 v[8:9], v[8:9], v[138:139], v[24:25] op_sel_hi:[1,0,1] neg_lo:[0,0,1] neg_hi:[0,0,1]
	v_pk_fma_f32 v[10:11], v[10:11], v[138:139], v[26:27] op_sel_hi:[1,0,1] neg_lo:[0,0,1] neg_hi:[0,0,1]
	v_add_f32_e32 v138, v142, v143
	global_load_dwordx4 v[100:103], v168, s[38:39]
	global_load_dwordx4 v[96:99], v168, s[38:39] offset:32
	v_add_f32_e32 v138, v144, v138
	v_pk_mul_f32 v[146:147], v[114:115], v[114:115]
	v_add_f32_e32 v138, v145, v138
	v_add_f32_e32 v138, v146, v138
	v_pk_mul_f32 v[148:149], v[118:119], v[118:119]
	v_add_f32_e32 v138, v147, v138
	v_add_f32_e32 v138, v148, v138
	v_pk_mul_f32 v[150:151], v[116:117], v[116:117]
	v_add_f32_e32 v138, v149, v138
	global_load_dwordx4 v[104:107], v168, s[38:39] offset:64
	global_load_dwordx4 v[12:15], v168, s[38:39] offset:96
	v_add_f32_e32 v138, v150, v138
	v_pk_mul_f32 v[152:153], v[122:123], v[122:123]
	v_add_f32_e32 v138, v151, v138
	v_add_f32_e32 v138, v152, v138
	v_pk_mul_f32 v[124:125], v[120:121], v[120:121]
	v_add_f32_e32 v138, v153, v138
	v_add_f32_e32 v124, v124, v138
	v_pk_mul_f32 v[110:111], v[108:109], v[108:109]
	v_add_f32_e32 v124, v125, v124
	v_add_f32_e32 v110, v110, v124
	v_pk_mul_f32 v[126:127], v[80:81], v[80:81]
	v_add_f32_e32 v110, v111, v110
	v_add_f32_e32 v110, v126, v110
	v_pk_mul_f32 v[154:155], v[82:83], v[82:83]
	v_add_f32_e32 v110, v127, v110
	v_add_f32_e32 v110, v154, v110
	v_pk_mul_f32 v[156:157], v[84:85], v[84:85]
	v_add_f32_e32 v110, v155, v110
	v_add_f32_e32 v110, v156, v110
	v_pk_mul_f32 v[158:159], v[86:87], v[86:87]
	v_add_f32_e32 v110, v157, v110
	v_add_f32_e32 v110, v158, v110
	v_pk_mul_f32 v[160:161], v[88:89], v[88:89]
	v_add_f32_e32 v110, v159, v110
	v_add_f32_e32 v110, v160, v110
	v_pk_mul_f32 v[162:163], v[90:91], v[90:91]
	v_add_f32_e32 v110, v161, v110
	v_add_f32_e32 v110, v162, v110
	v_pk_mul_f32 v[92:93], v[76:77], v[76:77]
	v_add_f32_e32 v110, v163, v110
	v_add_f32_e32 v92, v92, v110
	v_pk_mul_f32 v[94:95], v[78:79], v[78:79]
	v_add_f32_e32 v92, v93, v92
	v_add_f32_e32 v92, v94, v92
	v_pk_mul_f32 v[164:165], v[48:49], v[48:49]
	v_add_f32_e32 v92, v95, v92
	v_add_f32_e32 v92, v164, v92
	v_pk_mul_f32 v[166:167], v[50:51], v[50:51]
	v_add_f32_e32 v92, v165, v92
	v_add_f32_e32 v92, v166, v92
	v_pk_mul_f32 v[52:53], v[36:37], v[36:37]
	v_add_f32_e32 v92, v167, v92
	v_add_f32_e32 v52, v52, v92
	v_pk_mul_f32 v[54:55], v[38:39], v[38:39]
	v_add_f32_e32 v52, v53, v52
	v_add_f32_e32 v52, v54, v52
	v_pk_mul_f32 v[56:57], v[40:41], v[40:41]
	v_add_f32_e32 v52, v55, v52
	v_add_f32_e32 v52, v56, v52
	v_pk_mul_f32 v[58:59], v[42:43], v[42:43]
	v_add_f32_e32 v52, v57, v52
	v_add_f32_e32 v52, v58, v52
	v_pk_mul_f32 v[60:61], v[44:45], v[44:45]
	v_add_f32_e32 v52, v59, v52
	v_add_f32_e32 v52, v60, v52
	v_pk_mul_f32 v[62:63], v[46:47], v[46:47]
	v_add_f32_e32 v52, v61, v52
	v_add_f32_e32 v52, v62, v52
	v_pk_mul_f32 v[16:17], v[0:1], v[0:1]
	v_add_f32_e32 v52, v63, v52
	v_add_f32_e32 v16, v16, v52
	v_pk_mul_f32 v[18:19], v[2:3], v[2:3]
	v_add_f32_e32 v16, v17, v16
	v_add_f32_e32 v16, v18, v16
	v_pk_mul_f32 v[20:21], v[4:5], v[4:5]
	v_add_f32_e32 v16, v19, v16
	v_add_f32_e32 v16, v20, v16
	v_pk_mul_f32 v[22:23], v[6:7], v[6:7]
	v_add_f32_e32 v16, v21, v16
	v_add_f32_e32 v16, v22, v16
	v_pk_mul_f32 v[24:25], v[8:9], v[8:9]
	v_add_f32_e32 v16, v23, v16
	v_add_f32_e32 v16, v24, v16
	v_pk_mul_f32 v[26:27], v[10:11], v[10:11]
	v_add_f32_e32 v16, v25, v16
	v_add_f32_e32 v16, v26, v16
	v_add_f32_e32 v16, v27, v16
	v_add_f32_e32 v16, v134, v16
	v_add_f32_e32 v16, v135, v16
	v_add_f32_e32 v16, v136, v16
	v_add_f32_e32 v16, v137, v16
	ds_bpermute_b32 v17, v213, v16
	global_load_dwordx4 v[64:67], v168, s[38:39] offset:128
	global_load_dwordx4 v[28:31], v168, s[38:39] offset:160
	global_load_dwordx4 v[72:75], v168, s[38:39] offset:192
	global_load_dwordx4 v[68:71], v168, s[38:39] offset:224
	v_lshlrev_b32_e32 v18, 11, v139
	v_and_b32_e32 v18, 0xf800, v18
	s_waitcnt lgkmcnt(0)
	v_add_f32_e32 v16, v16, v17
	v_fmamk_f32 v16, v16, 0x3c000000, v216
	v_mul_f32_e32 v17, 0x4b800000, v16
	v_cmp_gt_f32_e32 vcc, s23, v16
	v_lshl_or_b32 v110, v141, 3, v18
	v_mbcnt_lo_u32_b32 v250, -1, 0
	v_mbcnt_hi_u32_b32 v250, -1, v250
	v_and_b32_e32 v250, 32, v250
	v_lshrrev_b32_e32 v250, 2, v250
	v_add_u32_e32 v110, v110, v250
	global_load_dwordx4 v[32:35], v168, s[38:39] offset:256
	global_load_dwordx4 v[18:21], v168, s[38:39] offset:288
	v_cndmask_b32_e32 v16, v16, v17, vcc
	v_rsq_f32_e32 v16, v16
	global_load_dwordx4 v[22:25], v168, s[38:39] offset:320
	global_load_dwordx4 v[52:55], v168, s[38:39] offset:352
	global_load_dwordx4 v[56:59], v168, s[38:39] offset:384
	global_load_dwordx4 v[60:63], v168, s[38:39] offset:416
	v_mul_f32_e32 v17, 0x45800000, v16
	v_cndmask_b32_e32 v16, v16, v17, vcc
	v_mul_f32_e32 v16, 0x3f4ccccd, v16
	v_pk_mul_f32 v[26:27], v[112:113], v[16:17] op_sel_hi:[1,0]
	v_pk_mul_f32 v[92:93], v[132:133], v[16:17] op_sel_hi:[1,0]
	s_waitcnt vmcnt(0)
; DI unsigned pk2(float lo, float hi) { bf2_t v = __builtin_convertvector((f32x2){lo, hi}, bf2_t); return __builtin_bit_cast(unsigned, v); }
; DI void dattn_unit2(const bf16_t* __restrict__ Qg, const bf16_t* __restrict__ Kg, const bf16_t* __restrict__ Vg, bf16_t* __restrict__ Og,
;                     int ntiles, int wave_tiles, float lam, const float* __restrict__ gsub, lds_t* shm) {
;     ...
; #pragma unroll
;   for (int c = 0; c < NC; ++c)
; #pragma unroll
;     for (int g4 = 0; g4 < 4; ++g4) {
;       const int dv0 = 32 * c + 8 * g4; f32x4 o;
; #pragma unroll
;       for (int e = 0; e < 4; ++e) o[e] = O[0][c][4 * g4 + e] * inv;
;       o = o * gld<f32x4>(gsub + dv0, 16u * h_f);
;       u32x2 w; w.x = pk2(o[0], o[1]); w.y = pk2(o[2], o[3]);
;       gst<u32x2>(Og + dv0, ooff, w);
;     }
	v_pk_mul_f32 v[26:27], v[100:101], v[26:27]
	v_pk_mul_f32 v[92:93], v[102:103], v[92:93]
	v_cvt_pk_bf16_f32 v218, v26, v27
	v_cvt_pk_bf16_f32 v219, v92, v93
	v_pk_mul_f32 v[26:27], v[114:115], v[16:17] op_sel_hi:[1,0]
	v_pk_mul_f32 v[92:93], v[118:119], v[16:17] op_sel_hi:[1,0]
	v_pk_mul_f32 v[26:27], v[96:97], v[26:27]
	v_pk_mul_f32 v[92:93], v[98:99], v[92:93]
	v_cvt_pk_bf16_f32 v220, v26, v27
	v_cvt_pk_bf16_f32 v221, v92, v93
	s_nop 1
	v_permlane32_swap_b32_e32 v218, v220
	v_permlane32_swap_b32_e32 v219, v221
	global_store_dwordx4 v110, v[218:221], s[4:5] sc0 sc1
	v_pk_mul_f32 v[26:27], v[116:117], v[16:17] op_sel_hi:[1,0]
	v_pk_mul_f32 v[92:93], v[122:123], v[16:17] op_sel_hi:[1,0]
	v_pk_mul_f32 v[26:27], v[104:105], v[26:27]
	v_pk_mul_f32 v[92:93], v[106:107], v[92:93]
	v_cvt_pk_bf16_f32 v222, v26, v27
	v_cvt_pk_bf16_f32 v223, v92, v93
	v_pk_mul_f32 v[26:27], v[120:121], v[16:17] op_sel_hi:[1,0]
	global_load_dwordx4 v[92:95], v168, s[38:39] offset:448
	v_pk_mul_f32 v[96:97], v[108:109], v[16:17] op_sel_hi:[1,0]
	v_pk_mul_f32 v[12:13], v[12:13], v[26:27]
	v_pk_mul_f32 v[14:15], v[14:15], v[96:97]
	v_cvt_pk_bf16_f32 v224, v12, v13
	v_cvt_pk_bf16_f32 v225, v14, v15
	s_nop 1
	v_permlane32_swap_b32_e32 v222, v224
	v_permlane32_swap_b32_e32 v223, v225
	global_store_dwordx4 v110, v[222:225], s[4:5] offset:32 sc0 sc1
	global_load_dwordx4 v[12:15], v168, s[38:39] offset:480
	v_pk_mul_f32 v[26:27], v[80:81], v[16:17] op_sel_hi:[1,0]
	v_pk_mul_f32 v[80:81], v[82:83], v[16:17] op_sel_hi:[1,0]
	v_pk_mul_f32 v[0:1], v[0:1], v[16:17] op_sel_hi:[1,0]
	v_pk_mul_f32 v[2:3], v[2:3], v[16:17] op_sel_hi:[1,0]
	s_andn2_b64 vcc, exec, s[40:41]
	v_pk_mul_f32 v[66:67], v[66:67], v[80:81]
	v_pk_mul_f32 v[26:27], v[64:65], v[26:27]
	v_pk_mul_f32 v[64:65], v[86:87], v[16:17] op_sel_hi:[1,0]
	v_cvt_pk_bf16_f32 v226, v26, v27
	v_cvt_pk_bf16_f32 v227, v66, v67
	v_pk_mul_f32 v[26:27], v[84:85], v[16:17] op_sel_hi:[1,0]
	v_pk_mul_f32 v[30:31], v[30:31], v[64:65]
	v_pk_mul_f32 v[26:27], v[28:29], v[26:27]
	v_pk_mul_f32 v[28:29], v[90:91], v[16:17] op_sel_hi:[1,0]
	v_cvt_pk_bf16_f32 v228, v26, v27
	v_cvt_pk_bf16_f32 v229, v30, v31
	s_nop 1
	v_permlane32_swap_b32_e32 v226, v228
	v_permlane32_swap_b32_e32 v227, v229
	global_store_dwordx4 v110, v[226:229], s[4:5] offset:64 sc0 sc1
	v_pk_mul_f32 v[26:27], v[88:89], v[16:17] op_sel_hi:[1,0]
	v_pk_mul_f32 v[28:29], v[74:75], v[28:29]
	v_pk_mul_f32 v[26:27], v[72:73], v[26:27]
	v_pk_mul_f32 v[2:3], v[58:59], v[2:3]
	v_cvt_pk_bf16_f32 v230, v26, v27
	v_cvt_pk_bf16_f32 v231, v28, v29
	v_pk_mul_f32 v[26:27], v[76:77], v[16:17] op_sel_hi:[1,0]
	v_pk_mul_f32 v[28:29], v[78:79], v[16:17] op_sel_hi:[1,0]
	v_pk_mul_f32 v[26:27], v[68:69], v[26:27]
	v_pk_mul_f32 v[28:29], v[70:71], v[28:29]
	v_cvt_pk_bf16_f32 v232, v26, v27
	v_cvt_pk_bf16_f32 v233, v28, v29
	s_nop 1
	v_permlane32_swap_b32_e32 v230, v232
	v_permlane32_swap_b32_e32 v231, v233
	global_store_dwordx4 v110, v[230:233], s[4:5] offset:96 sc0 sc1
	v_pk_mul_f32 v[26:27], v[48:49], v[16:17] op_sel_hi:[1,0]
	v_pk_mul_f32 v[28:29], v[50:51], v[16:17] op_sel_hi:[1,0]
	v_pk_mul_f32 v[26:27], v[32:33], v[26:27]
	v_pk_mul_f32 v[28:29], v[34:35], v[28:29]
	v_pk_mul_f32 v[0:1], v[56:57], v[0:1]
	v_cvt_pk_bf16_f32 v234, v26, v27
	v_cvt_pk_bf16_f32 v235, v28, v29
	v_cvt_pk_bf16_f32 v242, v0, v1
	v_cvt_pk_bf16_f32 v243, v2, v3
	v_pk_mul_f32 v[26:27], v[36:37], v[16:17] op_sel_hi:[1,0]
	v_pk_mul_f32 v[28:29], v[38:39], v[16:17] op_sel_hi:[1,0]
	v_pk_mul_f32 v[0:1], v[4:5], v[16:17] op_sel_hi:[1,0]
	v_pk_mul_f32 v[2:3], v[6:7], v[16:17] op_sel_hi:[1,0]
	v_pk_mul_f32 v[20:21], v[20:21], v[28:29]
	v_pk_mul_f32 v[18:19], v[18:19], v[26:27]
	v_pk_mul_f32 v[2:3], v[62:63], v[2:3]
	v_pk_mul_f32 v[0:1], v[60:61], v[0:1]
	v_cvt_pk_bf16_f32 v236, v18, v19
	v_cvt_pk_bf16_f32 v237, v20, v21
	v_cvt_pk_bf16_f32 v244, v0, v1
	v_cvt_pk_bf16_f32 v245, v2, v3
	s_nop 1
	v_permlane32_swap_b32_e32 v234, v236
	v_permlane32_swap_b32_e32 v235, v237
	global_store_dwordx4 v110, v[234:237], s[4:5] offset:128 sc0 sc1
	v_pk_mul_f32 v[18:19], v[40:41], v[16:17] op_sel_hi:[1,0]
	v_pk_mul_f32 v[20:21], v[42:43], v[16:17] op_sel_hi:[1,0]
	s_nop 1
	v_permlane32_swap_b32_e32 v242, v244
	v_permlane32_swap_b32_e32 v243, v245
	global_store_dwordx4 v110, v[242:245], s[4:5] offset:192 sc0 sc1
	v_pk_mul_f32 v[0:1], v[8:9], v[16:17] op_sel_hi:[1,0]
	v_pk_mul_f32 v[2:3], v[10:11], v[16:17] op_sel_hi:[1,0]
	v_pk_mul_f32 v[20:21], v[24:25], v[20:21]
	v_pk_mul_f32 v[18:19], v[22:23], v[18:19]
	s_waitcnt vmcnt(6)
	v_pk_mul_f32 v[2:3], v[94:95], v[2:3]
	v_pk_mul_f32 v[0:1], v[92:93], v[0:1]
	v_cvt_pk_bf16_f32 v238, v18, v19
	v_cvt_pk_bf16_f32 v239, v20, v21
	v_cvt_pk_bf16_f32 v246, v0, v1
	v_cvt_pk_bf16_f32 v247, v2, v3
	v_pk_mul_f32 v[18:19], v[44:45], v[16:17] op_sel_hi:[1,0]
	v_pk_mul_f32 v[20:21], v[46:47], v[16:17] op_sel_hi:[1,0]
	v_pk_mul_f32 v[0:1], v[128:129], v[16:17] op_sel_hi:[1,0]
	v_pk_mul_f32 v[2:3], v[130:131], v[16:17] op_sel_hi:[1,0]
	v_pk_mul_f32 v[20:21], v[54:55], v[20:21]
	v_pk_mul_f32 v[18:19], v[52:53], v[18:19]
	s_waitcnt vmcnt(4)
	v_pk_mul_f32 v[2:3], v[14:15], v[2:3]
	v_pk_mul_f32 v[0:1], v[12:13], v[0:1]
	v_cvt_pk_bf16_f32 v240, v18, v19
	v_cvt_pk_bf16_f32 v241, v20, v21
	v_cvt_pk_bf16_f32 v248, v0, v1
	v_cvt_pk_bf16_f32 v249, v2, v3
	s_nop 1
	v_permlane32_swap_b32_e32 v238, v240
	v_permlane32_swap_b32_e32 v239, v241
	global_store_dwordx4 v110, v[238:241], s[4:5] offset:160 sc0 sc1
	s_nop 1
	v_permlane32_swap_b32_e32 v246, v248
	v_permlane32_swap_b32_e32 v247, v249
	global_store_dwordx4 v110, v[246:249], s[4:5] offset:224 sc0 sc1
	s_mov_b64 s[4:5], 0
	s_cbranch_vccz .LBB0_406
